# P1 norm output stores write-through (sc1): nothing dirty left for the barrier's L2 writeback after phase 1
# baseline (speedup 1.0000x reference)
; __device__ __forceinline__ void norm_mod_phase(const float* X, const float* ng, const float* mod, bf16* H, int G) {
;     int tid = threadIdx.x; asm volatile("" : "+v"(tid)); const int lane = tid & 63, wave = tid >> 6;
;     const int gw = blockIdx.x * NWAVES + wave, NGW = G * NWAVES;
; #pragma unroll 1
;     for (int b = 0; b < 2; ++b) {
;         f32x4 gs[4], sh[4];
; #pragma unroll
;         for (int j = 0; j < 4; ++j) { const int c = 4 * lane + 256 * j; gs[j] = *(const f32x4*)(ng + c) * (*(const f32x4*)(mod + b * 3072 + 1024 + c) + 1.0f); sh[j] = *(const f32x4*)(mod + b * 3072 + c); }
;         for (int tb = gw; tb < SEQL; tb += 4 * NGW) {
;             f32x4 v[4][4]; float s[4]; int mr[4]; bool has[4];
; #pragma unroll
;             for (int r = 0; r < 4; ++r) { const int t = tb + r * NGW; has[r] = t < SEQL; mr[r] = b * SEQL + (has[r] ? t : tb); const f32x4* xr = (const f32x4*)(X + (size_t)mr[r] * D) + lane;
; #pragma unroll
;                 for (int j = 0; j < 4; ++j) v[r][j] = xr[64 * j]; }
.LBB0_85:
	s_or_b64 exec, exec, s[12:13]
	s_waitcnt lgkmcnt(0)
	v_mov_b32_e32 v0, v216
	s_barrier
	s_add_u32 s12, s10, 0x1800000
	v_and_b32_e32 v1, 63, v0
	v_ashrrev_i32_e32 v0, 6, v0
	v_readlane_b32 s3, v249, 3
	v_mov_b32_e32 v3, 0
	s_addc_u32 s13, s11, 0
	v_add_u32_e32 v110, s3, v0
	v_lshlrev_b32_e32 v0, 2, v1
	v_lshlrev_b32_e32 v2, 4, v1
	v_lshlrev_b32_e32 v4, 3, v1
	v_mov_b32_e32 v5, v3
	v_lshl_add_u64 v[80:81], s[68:69], 0, v[2:3]
	v_lshl_add_u64 v[82:83], s[12:13], 0, v[4:5]
	v_lshl_add_u64 v[84:85], s[72:73], 0, v[2:3]
	v_or_b32_e32 v2, 0x100, v0
	v_or_b32_e32 v4, 0x200, v0
	v_or_b32_e32 v6, 0x300, v0
	v_lshlrev_b32_e32 v111, 2, v0
	v_mbcnt_lo_u32_b32 v0, -1, 0
	v_mbcnt_hi_u32_b32 v208, -1, v0
	s_movk_i32 s3, 0x2000
	s_add_i32 s7, s4, s4
	v_and_b32_e32 v217, 64, v208
	v_cmp_gt_i32_e64 s[36:37], s3, v110
	s_lshl_b32 s5, s6, 4
	s_mov_b32 s21, 0
	s_mov_b64 s[22:23], -1
	v_lshlrev_b32_e32 v112, 2, v2
	v_lshlrev_b32_e32 v113, 2, v4
	v_lshlrev_b32_e32 v114, 2, v6
	v_mov_b32_e32 v115, 0x358637bd
	s_add_i32 s7, s7, s4
	v_add_u32_e32 v209, 64, v217
	v_xor_b32_e32 v215, 1, v208
	v_xor_b32_e32 v214, 2, v208
	v_xor_b32_e32 v213, 4, v208
	v_xor_b32_e32 v212, 8, v208
	v_xor_b32_e32 v211, 16, v208
	v_xor_b32_e32 v210, 32, v208
	s_cmp_eq_u32 s6, 0x100
	s_cbranch_scc0 .Lnorm_orig
	v_lshlrev_b32_e32 v107, 4, v208
	v_lshlrev_b32_e32 v106, 3, v208
	v_readfirstlane_b32 s16, v110
	s_lshl_b32 s14, s6, 3
	s_add_u32 s38, s0, 0x1000
	s_addc_u32 s39, s1, 0
	s_add_u32 s40, s0, 0x3000
	s_addc_u32 s41, s1, 0
	s_add_u32 s42, s0, 0x4000
	s_addc_u32 s43, s1, 0
	global_load_dwordx4 v[0:3], v107, s[72:73]
	global_load_dwordx4 v[4:7], v107, s[72:73] offset:1024
	global_load_dwordx4 v[8:11], v107, s[72:73] offset:2048
	global_load_dwordx4 v[12:15], v107, s[72:73] offset:3072
	global_load_dwordx4 v[16:19], v107, s[38:39]
	global_load_dwordx4 v[20:23], v107, s[38:39] offset:1024
	global_load_dwordx4 v[24:27], v107, s[38:39] offset:2048
	global_load_dwordx4 v[28:31], v107, s[38:39] offset:3072
	global_load_dwordx4 v[32:35], v107, s[0:1]
	global_load_dwordx4 v[36:39], v107, s[0:1] offset:1024
	global_load_dwordx4 v[40:43], v107, s[0:1] offset:2048
	global_load_dwordx4 v[44:47], v107, s[0:1] offset:3072
	global_load_dwordx4 v[48:51], v107, s[42:43]
	global_load_dwordx4 v[52:55], v107, s[42:43] offset:1024
	global_load_dwordx4 v[56:59], v107, s[42:43] offset:2048
	global_load_dwordx4 v[60:63], v107, s[42:43] offset:3072
	global_load_dwordx4 v[64:67], v107, s[40:41]
	global_load_dwordx4 v[68:71], v107, s[40:41] offset:1024
	global_load_dwordx4 v[72:75], v107, s[40:41] offset:2048
	global_load_dwordx4 v[76:79], v107, s[40:41] offset:3072
	s_mov_b32 s18, s16
	s_lshl_b32 s20, s18, 12
	s_add_u32 s22, s68, s20
	s_addc_u32 s23, s69, 0
	global_load_dwordx4 v[116:119], v107, s[22:23]
	global_load_dwordx4 v[120:123], v107, s[22:23] offset:1024
	global_load_dwordx4 v[124:127], v107, s[22:23] offset:2048
	global_load_dwordx4 v[128:131], v107, s[22:23] offset:3072
	s_add_i32 s18, s18, s14
	s_lshl_b32 s20, s18, 12
	s_add_u32 s22, s68, s20
	s_addc_u32 s23, s69, 0
	global_load_dwordx4 v[132:135], v107, s[22:23]
	global_load_dwordx4 v[136:139], v107, s[22:23] offset:1024
	global_load_dwordx4 v[140:143], v107, s[22:23] offset:2048
	global_load_dwordx4 v[144:147], v107, s[22:23] offset:3072
	s_add_i32 s18, s18, s14
	s_lshl_b32 s20, s18, 12
	s_add_u32 s22, s68, s20
	s_addc_u32 s23, s69, 0
	global_load_dwordx4 v[148:151], v107, s[22:23]
	global_load_dwordx4 v[152:155], v107, s[22:23] offset:1024
	global_load_dwordx4 v[156:159], v107, s[22:23] offset:2048
	global_load_dwordx4 v[160:163], v107, s[22:23] offset:3072
	s_add_i32 s18, s18, s14
	s_lshl_b32 s20, s18, 12
	s_add_u32 s22, s68, s20
	s_addc_u32 s23, s69, 0
	global_load_dwordx4 v[164:167], v107, s[22:23]
	global_load_dwordx4 v[168:171], v107, s[22:23] offset:1024
	global_load_dwordx4 v[172:175], v107, s[22:23] offset:2048
	global_load_dwordx4 v[176:179], v107, s[22:23] offset:3072
	s_add_i32 s18, s16, 8192
	s_lshl_b32 s20, s18, 12
	s_add_u32 s22, s68, s20
	s_addc_u32 s23, s69, 0
	global_load_dwordx4 v[180:183], v107, s[22:23]
	global_load_dwordx4 v[184:187], v107, s[22:23] offset:1024
	global_load_dwordx4 v[188:191], v107, s[22:23] offset:2048
	global_load_dwordx4 v[192:195], v107, s[22:23] offset:3072
	s_add_i32 s18, s18, s14
	s_lshl_b32 s20, s18, 12
	s_add_u32 s22, s68, s20
	s_addc_u32 s23, s69, 0
	global_load_dwordx4 v[86:89], v107, s[22:23]
	global_load_dwordx4 v[90:93], v107, s[22:23] offset:1024
	global_load_dwordx4 v[94:97], v107, s[22:23] offset:2048
	global_load_dwordx4 v[98:101], v107, s[22:23] offset:3072
	s_add_i32 s18, s18, s14
	s_lshl_b32 s20, s18, 12
	s_add_u32 s22, s68, s20
	s_addc_u32 s23, s69, 0
	global_load_dwordx4 v[218:221], v107, s[22:23]
	global_load_dwordx4 v[222:225], v107, s[22:23] offset:1024
	global_load_dwordx4 v[226:229], v107, s[22:23] offset:2048
	global_load_dwordx4 v[230:233], v107, s[22:23] offset:3072
	s_add_i32 s18, s18, s14
	s_lshl_b32 s20, s18, 12
	s_add_u32 s22, s68, s20
	s_addc_u32 s23, s69, 0
	global_load_dwordx4 v[196:199], v107, s[22:23]
	global_load_dwordx4 v[200:203], v107, s[22:23] offset:1024
	global_load_dwordx4 v[204:207], v107, s[22:23] offset:2048
	global_load_dwordx4 v[102:105], v107, s[22:23] offset:3072
	v_xor_b32_e32 v242, 1, v208
	v_lshlrev_b32_e32 v242, 2, v242
	v_xor_b32_e32 v243, 2, v208
	v_lshlrev_b32_e32 v243, 2, v243
	v_xor_b32_e32 v244, 4, v208
	v_lshlrev_b32_e32 v244, 2, v244
	v_xor_b32_e32 v245, 8, v208
	v_lshlrev_b32_e32 v245, 2, v245
	v_xor_b32_e32 v246, 16, v208
	v_lshlrev_b32_e32 v246, 2, v246
	v_xor_b32_e32 v247, 32, v208
	v_lshlrev_b32_e32 v247, 2, v247
	v_mov_b32_e32 v108, 0x358637bd
	s_waitcnt vmcnt(32)
; __device__ __forceinline__ void norm_mod_phase(const float* X, const float* ng, const float* mod, bf16* H, int G) {
;     ...
;         for (int j = 0; j < 4; ++j) { const int c = 4 * lane + 256 * j; gs[j] = *(const f32x4*)(ng + c) * (*(const f32x4*)(mod + b * 3072 + 1024 + c) + 1.0f); sh[j] = *(const f32x4*)(mod + b * 3072 + c); }
;         for (int tb = gw; tb < SEQL; tb += 4 * NGW) {
;             f32x4 v[4][4]; float s[4]; int mr[4]; bool has[4];
; #pragma unroll
;             for (int r = 0; r < 4; ++r) { const int t = tb + r * NGW; has[r] = t < SEQL; mr[r] = b * SEQL + (has[r] ? t : tb); const f32x4* xr = (const f32x4*)(X + (size_t)mr[r] * D) + lane;
; #pragma unroll
;                 for (int j = 0; j < 4; ++j) v[r][j] = xr[64 * j]; }
; #pragma unroll
;             for (int r = 0; r < 4; ++r) { float q = 0.f;
; #pragma unroll
;                 for (int j = 0; j < 4; ++j) q += (v[r][j].x * v[r][j].x + v[r][j].y * v[r][j].y) + (v[r][j].z * v[r][j].z + v[r][j].w * v[r][j].w);
;                 s[r] = q; }
	v_add_f32_e32 v16, 1.0, v16
	v_add_f32_e32 v17, 1.0, v17
	v_add_f32_e32 v18, 1.0, v18
	v_add_f32_e32 v19, 1.0, v19
	v_add_f32_e32 v20, 1.0, v20
	v_add_f32_e32 v21, 1.0, v21
	v_add_f32_e32 v22, 1.0, v22
	v_add_f32_e32 v23, 1.0, v23
	v_add_f32_e32 v24, 1.0, v24
	v_add_f32_e32 v25, 1.0, v25
	v_add_f32_e32 v26, 1.0, v26
	v_add_f32_e32 v27, 1.0, v27
	v_add_f32_e32 v28, 1.0, v28
	v_add_f32_e32 v29, 1.0, v29
	v_add_f32_e32 v30, 1.0, v30
	v_add_f32_e32 v31, 1.0, v31
	v_mul_f32_e32 v16, v0, v16
	v_mul_f32_e32 v17, v1, v17
	v_mul_f32_e32 v18, v2, v18
	v_mul_f32_e32 v19, v3, v19
	v_mul_f32_e32 v20, v4, v20
	v_mul_f32_e32 v21, v5, v21
	v_mul_f32_e32 v22, v6, v22
	v_mul_f32_e32 v23, v7, v23
	v_mul_f32_e32 v24, v8, v24
	v_mul_f32_e32 v25, v9, v25
	v_mul_f32_e32 v26, v10, v26
	v_mul_f32_e32 v27, v11, v27
	v_mul_f32_e32 v28, v12, v28
	v_mul_f32_e32 v29, v13, v29
	v_mul_f32_e32 v30, v14, v30
	v_mul_f32_e32 v31, v15, v31
	v_add_f32_e32 v48, 1.0, v48
	v_add_f32_e32 v49, 1.0, v49
	v_add_f32_e32 v50, 1.0, v50
	v_add_f32_e32 v51, 1.0, v51
	v_add_f32_e32 v52, 1.0, v52
	v_add_f32_e32 v53, 1.0, v53
	v_add_f32_e32 v54, 1.0, v54
	v_add_f32_e32 v55, 1.0, v55
	v_add_f32_e32 v56, 1.0, v56
	v_add_f32_e32 v57, 1.0, v57
	v_add_f32_e32 v58, 1.0, v58
	v_add_f32_e32 v59, 1.0, v59
	v_add_f32_e32 v60, 1.0, v60
	v_add_f32_e32 v61, 1.0, v61
	v_add_f32_e32 v62, 1.0, v62
	v_add_f32_e32 v63, 1.0, v63
	v_mul_f32_e32 v48, v0, v48
	v_mul_f32_e32 v49, v1, v49
	v_mul_f32_e32 v50, v2, v50
	v_mul_f32_e32 v51, v3, v51
	v_mul_f32_e32 v52, v4, v52
	v_mul_f32_e32 v53, v5, v53
	v_mul_f32_e32 v54, v6, v54
	v_mul_f32_e32 v55, v7, v55
	v_mul_f32_e32 v56, v8, v56
	v_mul_f32_e32 v57, v9, v57
	v_mul_f32_e32 v58, v10, v58
	v_mul_f32_e32 v59, v11, v59
	v_mul_f32_e32 v60, v12, v60
	v_mul_f32_e32 v61, v13, v61
	v_mul_f32_e32 v62, v14, v62
	v_mul_f32_e32 v63, v15, v63
	s_waitcnt vmcnt(28)
	v_mul_f32_e32 v250, v116, v116
	v_mul_f32_e32 v251, v118, v118
	v_fmac_f32_e32 v250, v117, v117
	v_fmac_f32_e32 v251, v119, v119
	v_add_f32_e32 v234, v250, v251
	v_mul_f32_e32 v250, v120, v120
	v_mul_f32_e32 v251, v122, v122
	v_fmac_f32_e32 v250, v121, v121
	v_fmac_f32_e32 v251, v123, v123
	v_add_f32_e32 v250, v250, v251
	v_add_f32_e32 v234, v234, v250
	v_mul_f32_e32 v250, v124, v124
	v_mul_f32_e32 v251, v126, v126
	v_fmac_f32_e32 v250, v125, v125
	v_fmac_f32_e32 v251, v127, v127
	v_add_f32_e32 v250, v250, v251
	v_add_f32_e32 v234, v234, v250
	v_mul_f32_e32 v250, v128, v128
	v_mul_f32_e32 v251, v130, v130
	v_fmac_f32_e32 v250, v129, v129
	v_fmac_f32_e32 v251, v131, v131
	v_add_f32_e32 v250, v250, v251
	v_add_f32_e32 v234, v234, v250
	s_waitcnt vmcnt(24)
	v_mul_f32_e32 v250, v132, v132
	v_mul_f32_e32 v251, v134, v134
	v_fmac_f32_e32 v250, v133, v133
	v_fmac_f32_e32 v251, v135, v135
	v_add_f32_e32 v235, v250, v251
	v_mul_f32_e32 v250, v136, v136
	v_mul_f32_e32 v251, v138, v138
	v_fmac_f32_e32 v250, v137, v137
	v_fmac_f32_e32 v251, v139, v139
	v_add_f32_e32 v250, v250, v251
	v_add_f32_e32 v235, v235, v250
	v_mul_f32_e32 v250, v140, v140
	v_mul_f32_e32 v251, v142, v142
	v_fmac_f32_e32 v250, v141, v141
	v_fmac_f32_e32 v251, v143, v143
	v_add_f32_e32 v250, v250, v251
	v_add_f32_e32 v235, v235, v250
	v_mul_f32_e32 v250, v144, v144
	v_mul_f32_e32 v251, v146, v146
	v_fmac_f32_e32 v250, v145, v145
	v_fmac_f32_e32 v251, v147, v147
	v_add_f32_e32 v250, v250, v251
	v_add_f32_e32 v235, v235, v250
	s_waitcnt vmcnt(20)
	v_mul_f32_e32 v250, v148, v148
	v_mul_f32_e32 v251, v150, v150
	v_fmac_f32_e32 v250, v149, v149
	v_fmac_f32_e32 v251, v151, v151
	v_add_f32_e32 v236, v250, v251
	v_mul_f32_e32 v250, v152, v152
	v_mul_f32_e32 v251, v154, v154
	v_fmac_f32_e32 v250, v153, v153
	v_fmac_f32_e32 v251, v155, v155
	v_add_f32_e32 v250, v250, v251
	v_add_f32_e32 v236, v236, v250
	v_mul_f32_e32 v250, v156, v156
	v_mul_f32_e32 v251, v158, v158
	v_fmac_f32_e32 v250, v157, v157
	v_fmac_f32_e32 v251, v159, v159
	v_add_f32_e32 v250, v250, v251
	v_add_f32_e32 v236, v236, v250
	v_mul_f32_e32 v250, v160, v160
	v_mul_f32_e32 v251, v162, v162
	v_fmac_f32_e32 v250, v161, v161
	v_fmac_f32_e32 v251, v163, v163
	v_add_f32_e32 v250, v250, v251
	v_add_f32_e32 v236, v236, v250
	s_waitcnt vmcnt(16)
	v_mul_f32_e32 v250, v164, v164
	v_mul_f32_e32 v251, v166, v166
	v_fmac_f32_e32 v250, v165, v165
	v_fmac_f32_e32 v251, v167, v167
	v_add_f32_e32 v237, v250, v251
	v_mul_f32_e32 v250, v168, v168
	v_mul_f32_e32 v251, v170, v170
	v_fmac_f32_e32 v250, v169, v169
	v_fmac_f32_e32 v251, v171, v171
	v_add_f32_e32 v250, v250, v251
	v_add_f32_e32 v237, v237, v250
	v_mul_f32_e32 v250, v172, v172
	v_mul_f32_e32 v251, v174, v174
	v_fmac_f32_e32 v250, v173, v173
	v_fmac_f32_e32 v251, v175, v175
	v_add_f32_e32 v250, v250, v251
	v_add_f32_e32 v237, v237, v250
	v_mul_f32_e32 v250, v176, v176
	v_mul_f32_e32 v251, v178, v178
	v_fmac_f32_e32 v250, v177, v177
	v_fmac_f32_e32 v251, v179, v179
	v_add_f32_e32 v250, v250, v251
	v_add_f32_e32 v237, v237, v250
	s_waitcnt vmcnt(12)
	v_mul_f32_e32 v250, v180, v180
	v_mul_f32_e32 v251, v182, v182
	v_fmac_f32_e32 v250, v181, v181
	v_fmac_f32_e32 v251, v183, v183
	v_add_f32_e32 v238, v250, v251
	v_mul_f32_e32 v250, v184, v184
	v_mul_f32_e32 v251, v186, v186
	v_fmac_f32_e32 v250, v185, v185
	v_fmac_f32_e32 v251, v187, v187
	v_add_f32_e32 v250, v250, v251
	v_add_f32_e32 v238, v238, v250
	v_mul_f32_e32 v250, v188, v188
	v_mul_f32_e32 v251, v190, v190
	v_fmac_f32_e32 v250, v189, v189
	v_fmac_f32_e32 v251, v191, v191
	v_add_f32_e32 v250, v250, v251
	v_add_f32_e32 v238, v238, v250
	v_mul_f32_e32 v250, v192, v192
	v_mul_f32_e32 v251, v194, v194
	v_fmac_f32_e32 v250, v193, v193
	v_fmac_f32_e32 v251, v195, v195
	v_add_f32_e32 v250, v250, v251
	v_add_f32_e32 v238, v238, v250
	s_waitcnt vmcnt(8)
; __device__ __forceinline__ void norm_mod_phase(const float* X, const float* ng, const float* mod, bf16* H, int G) {
;     ...
;             for (int r = 0; r < 4; ++r) { float q = 0.f;
; #pragma unroll
;                 for (int j = 0; j < 4; ++j) q += (v[r][j].x * v[r][j].x + v[r][j].y * v[r][j].y) + (v[r][j].z * v[r][j].z + v[r][j].w * v[r][j].w);
;                 s[r] = q; }
; #pragma unroll
;             for (int o = 1; o < 64; o <<= 1) {
; #pragma unroll
;                 for (int r = 0; r < 4; ++r) s[r] += __shfl_xor(s[r], o); }
	v_mul_f32_e32 v250, v86, v86
	v_mul_f32_e32 v251, v88, v88
	v_fmac_f32_e32 v250, v87, v87
	v_fmac_f32_e32 v251, v89, v89
	v_add_f32_e32 v239, v250, v251
	v_mul_f32_e32 v250, v90, v90
	v_mul_f32_e32 v251, v92, v92
	v_fmac_f32_e32 v250, v91, v91
	v_fmac_f32_e32 v251, v93, v93
	v_add_f32_e32 v250, v250, v251
	v_add_f32_e32 v239, v239, v250
	v_mul_f32_e32 v250, v94, v94
	v_mul_f32_e32 v251, v96, v96
	v_fmac_f32_e32 v250, v95, v95
	v_fmac_f32_e32 v251, v97, v97
	v_add_f32_e32 v250, v250, v251
	v_add_f32_e32 v239, v239, v250
	v_mul_f32_e32 v250, v98, v98
	v_mul_f32_e32 v251, v100, v100
	v_fmac_f32_e32 v250, v99, v99
	v_fmac_f32_e32 v251, v101, v101
	v_add_f32_e32 v250, v250, v251
	v_add_f32_e32 v239, v239, v250
	s_waitcnt vmcnt(4)
	v_mul_f32_e32 v250, v218, v218
	v_mul_f32_e32 v251, v220, v220
	v_fmac_f32_e32 v250, v219, v219
	v_fmac_f32_e32 v251, v221, v221
	v_add_f32_e32 v240, v250, v251
	v_mul_f32_e32 v250, v222, v222
	v_mul_f32_e32 v251, v224, v224
	v_fmac_f32_e32 v250, v223, v223
	v_fmac_f32_e32 v251, v225, v225
	v_add_f32_e32 v250, v250, v251
	v_add_f32_e32 v240, v240, v250
	v_mul_f32_e32 v250, v226, v226
	v_mul_f32_e32 v251, v228, v228
	v_fmac_f32_e32 v250, v227, v227
	v_fmac_f32_e32 v251, v229, v229
	v_add_f32_e32 v250, v250, v251
	v_add_f32_e32 v240, v240, v250
	v_mul_f32_e32 v250, v230, v230
	v_mul_f32_e32 v251, v232, v232
	v_fmac_f32_e32 v250, v231, v231
	v_fmac_f32_e32 v251, v233, v233
	v_add_f32_e32 v250, v250, v251
	v_add_f32_e32 v240, v240, v250
	s_waitcnt vmcnt(0)
	v_mul_f32_e32 v250, v196, v196
	v_mul_f32_e32 v251, v198, v198
	v_fmac_f32_e32 v250, v197, v197
	v_fmac_f32_e32 v251, v199, v199
	v_add_f32_e32 v241, v250, v251
	v_mul_f32_e32 v250, v200, v200
	v_mul_f32_e32 v251, v202, v202
	v_fmac_f32_e32 v250, v201, v201
	v_fmac_f32_e32 v251, v203, v203
	v_add_f32_e32 v250, v250, v251
	v_add_f32_e32 v241, v241, v250
	v_mul_f32_e32 v250, v204, v204
	v_mul_f32_e32 v251, v206, v206
	v_fmac_f32_e32 v250, v205, v205
	v_fmac_f32_e32 v251, v207, v207
	v_add_f32_e32 v250, v250, v251
	v_add_f32_e32 v241, v241, v250
	v_mul_f32_e32 v250, v102, v102
	v_mul_f32_e32 v251, v104, v104
	v_fmac_f32_e32 v250, v103, v103
	v_fmac_f32_e32 v251, v105, v105
	v_add_f32_e32 v250, v250, v251
	v_add_f32_e32 v241, v241, v250
	ds_bpermute_b32 v109, v242, v234
	ds_bpermute_b32 v110, v242, v235
	ds_bpermute_b32 v111, v242, v236
	ds_bpermute_b32 v112, v242, v237
	ds_bpermute_b32 v113, v242, v238
	ds_bpermute_b32 v114, v242, v239
	ds_bpermute_b32 v252, v242, v240
	ds_bpermute_b32 v253, v242, v241
	s_waitcnt lgkmcnt(7)
	v_add_f32_e32 v234, v234, v109
	s_waitcnt lgkmcnt(6)
	v_add_f32_e32 v235, v235, v110
	s_waitcnt lgkmcnt(5)
	v_add_f32_e32 v236, v236, v111
	s_waitcnt lgkmcnt(4)
	v_add_f32_e32 v237, v237, v112
	s_waitcnt lgkmcnt(3)
	v_add_f32_e32 v238, v238, v113
	s_waitcnt lgkmcnt(2)
	v_add_f32_e32 v239, v239, v114
	s_waitcnt lgkmcnt(1)
	v_add_f32_e32 v240, v240, v252
	s_waitcnt lgkmcnt(0)
	v_add_f32_e32 v241, v241, v253
	ds_bpermute_b32 v109, v243, v234
	ds_bpermute_b32 v110, v243, v235
	ds_bpermute_b32 v111, v243, v236
	ds_bpermute_b32 v112, v243, v237
	ds_bpermute_b32 v113, v243, v238
	ds_bpermute_b32 v114, v243, v239
	ds_bpermute_b32 v252, v243, v240
	ds_bpermute_b32 v253, v243, v241
	s_waitcnt lgkmcnt(7)
	v_add_f32_e32 v234, v234, v109
	s_waitcnt lgkmcnt(6)
	v_add_f32_e32 v235, v235, v110
	s_waitcnt lgkmcnt(5)
	v_add_f32_e32 v236, v236, v111
	s_waitcnt lgkmcnt(4)
	v_add_f32_e32 v237, v237, v112
	s_waitcnt lgkmcnt(3)
	v_add_f32_e32 v238, v238, v113
	s_waitcnt lgkmcnt(2)
	v_add_f32_e32 v239, v239, v114
	s_waitcnt lgkmcnt(1)
	v_add_f32_e32 v240, v240, v252
	s_waitcnt lgkmcnt(0)
	v_add_f32_e32 v241, v241, v253
	ds_bpermute_b32 v109, v244, v234
	ds_bpermute_b32 v110, v244, v235
	ds_bpermute_b32 v111, v244, v236
	ds_bpermute_b32 v112, v244, v237
	ds_bpermute_b32 v113, v244, v238
	ds_bpermute_b32 v114, v244, v239
	ds_bpermute_b32 v252, v244, v240
	ds_bpermute_b32 v253, v244, v241
	s_waitcnt lgkmcnt(7)
	v_add_f32_e32 v234, v234, v109
	s_waitcnt lgkmcnt(6)
	v_add_f32_e32 v235, v235, v110
	s_waitcnt lgkmcnt(5)
	v_add_f32_e32 v236, v236, v111
	s_waitcnt lgkmcnt(4)
	v_add_f32_e32 v237, v237, v112
	s_waitcnt lgkmcnt(3)
	v_add_f32_e32 v238, v238, v113
	s_waitcnt lgkmcnt(2)
	v_add_f32_e32 v239, v239, v114
	s_waitcnt lgkmcnt(1)
	v_add_f32_e32 v240, v240, v252
	s_waitcnt lgkmcnt(0)
	v_add_f32_e32 v241, v241, v253
	ds_bpermute_b32 v109, v245, v234
	ds_bpermute_b32 v110, v245, v235
	ds_bpermute_b32 v111, v245, v236
	ds_bpermute_b32 v112, v245, v237
	ds_bpermute_b32 v113, v245, v238
	ds_bpermute_b32 v114, v245, v239
	ds_bpermute_b32 v252, v245, v240
	ds_bpermute_b32 v253, v245, v241
	s_waitcnt lgkmcnt(7)
	v_add_f32_e32 v234, v234, v109
	s_waitcnt lgkmcnt(6)
	v_add_f32_e32 v235, v235, v110
	s_waitcnt lgkmcnt(5)
	v_add_f32_e32 v236, v236, v111
	s_waitcnt lgkmcnt(4)
	v_add_f32_e32 v237, v237, v112
	s_waitcnt lgkmcnt(3)
	v_add_f32_e32 v238, v238, v113
	s_waitcnt lgkmcnt(2)
	v_add_f32_e32 v239, v239, v114
	s_waitcnt lgkmcnt(1)
	v_add_f32_e32 v240, v240, v252
	s_waitcnt lgkmcnt(0)
	v_add_f32_e32 v241, v241, v253
	ds_bpermute_b32 v109, v246, v234
	ds_bpermute_b32 v110, v246, v235
	ds_bpermute_b32 v111, v246, v236
	ds_bpermute_b32 v112, v246, v237
	ds_bpermute_b32 v113, v246, v238
	ds_bpermute_b32 v114, v246, v239
	ds_bpermute_b32 v252, v246, v240
	ds_bpermute_b32 v253, v246, v241
	s_waitcnt lgkmcnt(7)
	v_add_f32_e32 v234, v234, v109
	s_waitcnt lgkmcnt(6)
	v_add_f32_e32 v235, v235, v110
	s_waitcnt lgkmcnt(5)
	v_add_f32_e32 v236, v236, v111
	s_waitcnt lgkmcnt(4)
	v_add_f32_e32 v237, v237, v112
	s_waitcnt lgkmcnt(3)
	v_add_f32_e32 v238, v238, v113
	s_waitcnt lgkmcnt(2)
; __device__ __forceinline__ unsigned pk2(float lo, float hi) { f32x2_t v = {lo, hi}; bf16x2_t b = __builtin_convertvector(v, bf16x2_t); return __builtin_bit_cast(unsigned, b); }
; __device__ __forceinline__ void norm_mod_phase(const float* X, const float* ng, const float* mod, bf16* H, int G) {
;     ...
;             for (int o = 1; o < 64; o <<= 1) {
; #pragma unroll
;                 for (int r = 0; r < 4; ++r) s[r] += __shfl_xor(s[r], o); }
; #pragma unroll
;             for (int r = 0; r < 4; ++r) { if (!has[r]) continue;
;                 const float rs = __builtin_amdgcn_rsqf(s[r] * (1.f / D) + EPSN); v2u* o8 = (v2u*)(H + (size_t)mr[r] * D) + lane;
; #pragma unroll
;                 for (int j = 0; j < 4; ++j) { const f32x4 h = v[r][j] * rs * gs[j] + sh[j]; o8[64 * j] = (v2u){pk2(h.x, h.y), pk2(h.z, h.w)}; } }
	v_add_f32_e32 v239, v239, v114
	s_waitcnt lgkmcnt(1)
	v_add_f32_e32 v240, v240, v252
	s_waitcnt lgkmcnt(0)
	v_add_f32_e32 v241, v241, v253
	ds_bpermute_b32 v109, v247, v234
	ds_bpermute_b32 v110, v247, v235
	ds_bpermute_b32 v111, v247, v236
	ds_bpermute_b32 v112, v247, v237
	ds_bpermute_b32 v113, v247, v238
	ds_bpermute_b32 v114, v247, v239
	ds_bpermute_b32 v252, v247, v240
	ds_bpermute_b32 v253, v247, v241
	s_waitcnt lgkmcnt(7)
	v_add_f32_e32 v234, v234, v109
	s_waitcnt lgkmcnt(6)
	v_add_f32_e32 v235, v235, v110
	s_waitcnt lgkmcnt(5)
	v_add_f32_e32 v236, v236, v111
	s_waitcnt lgkmcnt(4)
	v_add_f32_e32 v237, v237, v112
	s_waitcnt lgkmcnt(3)
	v_add_f32_e32 v238, v238, v113
	s_waitcnt lgkmcnt(2)
	v_add_f32_e32 v239, v239, v114
	s_waitcnt lgkmcnt(1)
	v_add_f32_e32 v240, v240, v252
	s_waitcnt lgkmcnt(0)
	v_add_f32_e32 v241, v241, v253
	v_fmamk_f32 v234, v234, 0x3a800000, v108
	v_fmamk_f32 v235, v235, 0x3a800000, v108
	v_fmamk_f32 v236, v236, 0x3a800000, v108
	v_fmamk_f32 v237, v237, 0x3a800000, v108
	v_fmamk_f32 v238, v238, 0x3a800000, v108
	v_fmamk_f32 v239, v239, 0x3a800000, v108
	v_fmamk_f32 v240, v240, 0x3a800000, v108
	v_fmamk_f32 v241, v241, 0x3a800000, v108
	v_rsq_f32_e32 v234, v234
	v_rsq_f32_e32 v235, v235
	v_rsq_f32_e32 v236, v236
	v_rsq_f32_e32 v237, v237
	v_rsq_f32_e32 v238, v238
	v_rsq_f32_e32 v239, v239
	v_rsq_f32_e32 v240, v240
	v_rsq_f32_e32 v241, v241
	s_nop 0
	s_mov_b32 s18, s16
	s_lshl_b32 s20, s18, 11
	s_add_u32 s22, s12, s20
	s_addc_u32 s23, s13, 0
	v_mul_f32_e32 v116, v116, v234
	v_mul_f32_e32 v117, v117, v234
	v_mul_f32_e32 v118, v118, v234
	v_mul_f32_e32 v119, v119, v234
	v_fma_f32 v116, v116, v16, v32
	v_fma_f32 v117, v117, v17, v33
	v_fma_f32 v118, v118, v18, v34
	v_fma_f32 v119, v119, v19, v35
	v_cvt_pk_bf16_f32 v116, v116, v117
	v_cvt_pk_bf16_f32 v117, v118, v119
	global_store_dwordx2 v106, v[116:117], s[22:23] sc1
	v_mul_f32_e32 v120, v120, v234
	v_mul_f32_e32 v121, v121, v234
	v_mul_f32_e32 v122, v122, v234
	v_mul_f32_e32 v123, v123, v234
	v_fma_f32 v120, v120, v20, v36
	v_fma_f32 v121, v121, v21, v37
	v_fma_f32 v122, v122, v22, v38
	v_fma_f32 v123, v123, v23, v39
	v_cvt_pk_bf16_f32 v120, v120, v121
	v_cvt_pk_bf16_f32 v121, v122, v123
	global_store_dwordx2 v106, v[120:121], s[22:23] offset:512 sc1
	v_mul_f32_e32 v124, v124, v234
	v_mul_f32_e32 v125, v125, v234
	v_mul_f32_e32 v126, v126, v234
	v_mul_f32_e32 v127, v127, v234
	v_fma_f32 v124, v124, v24, v40
	v_fma_f32 v125, v125, v25, v41
	v_fma_f32 v126, v126, v26, v42
	v_fma_f32 v127, v127, v27, v43
	v_cvt_pk_bf16_f32 v124, v124, v125
	v_cvt_pk_bf16_f32 v125, v126, v127
	global_store_dwordx2 v106, v[124:125], s[22:23] offset:1024 sc1
	v_mul_f32_e32 v128, v128, v234
	v_mul_f32_e32 v129, v129, v234
	v_mul_f32_e32 v130, v130, v234
	v_mul_f32_e32 v131, v131, v234
	v_fma_f32 v128, v128, v28, v44
	v_fma_f32 v129, v129, v29, v45
	v_fma_f32 v130, v130, v30, v46
	v_fma_f32 v131, v131, v31, v47
	v_cvt_pk_bf16_f32 v128, v128, v129
	v_cvt_pk_bf16_f32 v129, v130, v131
	global_store_dwordx2 v106, v[128:129], s[22:23] offset:1536 sc1
	s_add_i32 s18, s18, s14
	s_lshl_b32 s20, s18, 11
	s_add_u32 s22, s12, s20
	s_addc_u32 s23, s13, 0
	v_mul_f32_e32 v132, v132, v235
	v_mul_f32_e32 v133, v133, v235
	v_mul_f32_e32 v134, v134, v235
	v_mul_f32_e32 v135, v135, v235
	v_fma_f32 v132, v132, v16, v32
	v_fma_f32 v133, v133, v17, v33
	v_fma_f32 v134, v134, v18, v34
	v_fma_f32 v135, v135, v19, v35
	v_cvt_pk_bf16_f32 v132, v132, v133
	v_cvt_pk_bf16_f32 v133, v134, v135
	global_store_dwordx2 v106, v[132:133], s[22:23] sc1
	v_mul_f32_e32 v136, v136, v235
	v_mul_f32_e32 v137, v137, v235
	v_mul_f32_e32 v138, v138, v235
	v_mul_f32_e32 v139, v139, v235
	v_fma_f32 v136, v136, v20, v36
	v_fma_f32 v137, v137, v21, v37
	v_fma_f32 v138, v138, v22, v38
	v_fma_f32 v139, v139, v23, v39
	v_cvt_pk_bf16_f32 v136, v136, v137
	v_cvt_pk_bf16_f32 v137, v138, v139
	global_store_dwordx2 v106, v[136:137], s[22:23] offset:512 sc1
	v_mul_f32_e32 v140, v140, v235
	v_mul_f32_e32 v141, v141, v235
	v_mul_f32_e32 v142, v142, v235
	v_mul_f32_e32 v143, v143, v235
	v_fma_f32 v140, v140, v24, v40
	v_fma_f32 v141, v141, v25, v41
	v_fma_f32 v142, v142, v26, v42
	v_fma_f32 v143, v143, v27, v43
	v_cvt_pk_bf16_f32 v140, v140, v141
	v_cvt_pk_bf16_f32 v141, v142, v143
	global_store_dwordx2 v106, v[140:141], s[22:23] offset:1024 sc1
	v_mul_f32_e32 v144, v144, v235
	v_mul_f32_e32 v145, v145, v235
	v_mul_f32_e32 v146, v146, v235
	v_mul_f32_e32 v147, v147, v235
	v_fma_f32 v144, v144, v28, v44
	v_fma_f32 v145, v145, v29, v45
	v_fma_f32 v146, v146, v30, v46
	v_fma_f32 v147, v147, v31, v47
	v_cvt_pk_bf16_f32 v144, v144, v145
	v_cvt_pk_bf16_f32 v145, v146, v147
	global_store_dwordx2 v106, v[144:145], s[22:23] offset:1536 sc1
	s_add_i32 s18, s18, s14
	s_lshl_b32 s20, s18, 11
	s_add_u32 s22, s12, s20
	s_addc_u32 s23, s13, 0
	v_mul_f32_e32 v148, v148, v236
	v_mul_f32_e32 v149, v149, v236
	v_mul_f32_e32 v150, v150, v236
	v_mul_f32_e32 v151, v151, v236
	v_fma_f32 v148, v148, v16, v32
	v_fma_f32 v149, v149, v17, v33
	v_fma_f32 v150, v150, v18, v34
	v_fma_f32 v151, v151, v19, v35
	v_cvt_pk_bf16_f32 v148, v148, v149
	v_cvt_pk_bf16_f32 v149, v150, v151
	global_store_dwordx2 v106, v[148:149], s[22:23] sc1
	v_mul_f32_e32 v152, v152, v236
	v_mul_f32_e32 v153, v153, v236
	v_mul_f32_e32 v154, v154, v236
	v_mul_f32_e32 v155, v155, v236
	v_fma_f32 v152, v152, v20, v36
	v_fma_f32 v153, v153, v21, v37
	v_fma_f32 v154, v154, v22, v38
	v_fma_f32 v155, v155, v23, v39
	v_cvt_pk_bf16_f32 v152, v152, v153
	v_cvt_pk_bf16_f32 v153, v154, v155
	global_store_dwordx2 v106, v[152:153], s[22:23] offset:512 sc1
	v_mul_f32_e32 v156, v156, v236
	v_mul_f32_e32 v157, v157, v236
; __device__ __forceinline__ unsigned pk2(float lo, float hi) { f32x2_t v = {lo, hi}; bf16x2_t b = __builtin_convertvector(v, bf16x2_t); return __builtin_bit_cast(unsigned, b); }
; __device__ __forceinline__ void norm_mod_phase(const float* X, const float* ng, const float* mod, bf16* H, int G) {
;     ...
;             for (int r = 0; r < 4; ++r) { if (!has[r]) continue;
;                 const float rs = __builtin_amdgcn_rsqf(s[r] * (1.f / D) + EPSN); v2u* o8 = (v2u*)(H + (size_t)mr[r] * D) + lane;
; #pragma unroll
;                 for (int j = 0; j < 4; ++j) { const f32x4 h = v[r][j] * rs * gs[j] + sh[j]; o8[64 * j] = (v2u){pk2(h.x, h.y), pk2(h.z, h.w)}; } }
	v_mul_f32_e32 v158, v158, v236
	v_mul_f32_e32 v159, v159, v236
	v_fma_f32 v156, v156, v24, v40
	v_fma_f32 v157, v157, v25, v41
	v_fma_f32 v158, v158, v26, v42
	v_fma_f32 v159, v159, v27, v43
	v_cvt_pk_bf16_f32 v156, v156, v157
	v_cvt_pk_bf16_f32 v157, v158, v159
	global_store_dwordx2 v106, v[156:157], s[22:23] offset:1024 sc1
	v_mul_f32_e32 v160, v160, v236
	v_mul_f32_e32 v161, v161, v236
	v_mul_f32_e32 v162, v162, v236
	v_mul_f32_e32 v163, v163, v236
	v_fma_f32 v160, v160, v28, v44
	v_fma_f32 v161, v161, v29, v45
	v_fma_f32 v162, v162, v30, v46
	v_fma_f32 v163, v163, v31, v47
	v_cvt_pk_bf16_f32 v160, v160, v161
	v_cvt_pk_bf16_f32 v161, v162, v163
	global_store_dwordx2 v106, v[160:161], s[22:23] offset:1536 sc1
	s_add_i32 s18, s18, s14
	s_lshl_b32 s20, s18, 11
	s_add_u32 s22, s12, s20
	s_addc_u32 s23, s13, 0
	v_mul_f32_e32 v164, v164, v237
	v_mul_f32_e32 v165, v165, v237
	v_mul_f32_e32 v166, v166, v237
	v_mul_f32_e32 v167, v167, v237
	v_fma_f32 v164, v164, v16, v32
	v_fma_f32 v165, v165, v17, v33
	v_fma_f32 v166, v166, v18, v34
	v_fma_f32 v167, v167, v19, v35
	v_cvt_pk_bf16_f32 v164, v164, v165
	v_cvt_pk_bf16_f32 v165, v166, v167
	global_store_dwordx2 v106, v[164:165], s[22:23] sc1
	v_mul_f32_e32 v168, v168, v237
	v_mul_f32_e32 v169, v169, v237
	v_mul_f32_e32 v170, v170, v237
	v_mul_f32_e32 v171, v171, v237
	v_fma_f32 v168, v168, v20, v36
	v_fma_f32 v169, v169, v21, v37
	v_fma_f32 v170, v170, v22, v38
	v_fma_f32 v171, v171, v23, v39
	v_cvt_pk_bf16_f32 v168, v168, v169
	v_cvt_pk_bf16_f32 v169, v170, v171
	global_store_dwordx2 v106, v[168:169], s[22:23] offset:512 sc1
	v_mul_f32_e32 v172, v172, v237
	v_mul_f32_e32 v173, v173, v237
	v_mul_f32_e32 v174, v174, v237
	v_mul_f32_e32 v175, v175, v237
	v_fma_f32 v172, v172, v24, v40
	v_fma_f32 v173, v173, v25, v41
	v_fma_f32 v174, v174, v26, v42
	v_fma_f32 v175, v175, v27, v43
	v_cvt_pk_bf16_f32 v172, v172, v173
	v_cvt_pk_bf16_f32 v173, v174, v175
	global_store_dwordx2 v106, v[172:173], s[22:23] offset:1024 sc1
	v_mul_f32_e32 v176, v176, v237
	v_mul_f32_e32 v177, v177, v237
	v_mul_f32_e32 v178, v178, v237
	v_mul_f32_e32 v179, v179, v237
	v_fma_f32 v176, v176, v28, v44
	v_fma_f32 v177, v177, v29, v45
	v_fma_f32 v178, v178, v30, v46
	v_fma_f32 v179, v179, v31, v47
	v_cvt_pk_bf16_f32 v176, v176, v177
	v_cvt_pk_bf16_f32 v177, v178, v179
	global_store_dwordx2 v106, v[176:177], s[22:23] offset:1536 sc1
	s_add_i32 s18, s16, 8192
	s_lshl_b32 s20, s18, 11
	s_add_u32 s22, s12, s20
	s_addc_u32 s23, s13, 0
	v_mul_f32_e32 v180, v180, v238
	v_mul_f32_e32 v181, v181, v238
	v_mul_f32_e32 v182, v182, v238
	v_mul_f32_e32 v183, v183, v238
	v_fma_f32 v180, v180, v48, v64
	v_fma_f32 v181, v181, v49, v65
	v_fma_f32 v182, v182, v50, v66
	v_fma_f32 v183, v183, v51, v67
	v_cvt_pk_bf16_f32 v180, v180, v181
	v_cvt_pk_bf16_f32 v181, v182, v183
	global_store_dwordx2 v106, v[180:181], s[22:23] sc1
	v_mul_f32_e32 v184, v184, v238
	v_mul_f32_e32 v185, v185, v238
	v_mul_f32_e32 v186, v186, v238
	v_mul_f32_e32 v187, v187, v238
	v_fma_f32 v184, v184, v52, v68
	v_fma_f32 v185, v185, v53, v69
	v_fma_f32 v186, v186, v54, v70
	v_fma_f32 v187, v187, v55, v71
	v_cvt_pk_bf16_f32 v184, v184, v185
	v_cvt_pk_bf16_f32 v185, v186, v187
	global_store_dwordx2 v106, v[184:185], s[22:23] offset:512 sc1
	v_mul_f32_e32 v188, v188, v238
	v_mul_f32_e32 v189, v189, v238
	v_mul_f32_e32 v190, v190, v238
	v_mul_f32_e32 v191, v191, v238
	v_fma_f32 v188, v188, v56, v72
	v_fma_f32 v189, v189, v57, v73
	v_fma_f32 v190, v190, v58, v74
	v_fma_f32 v191, v191, v59, v75
	v_cvt_pk_bf16_f32 v188, v188, v189
	v_cvt_pk_bf16_f32 v189, v190, v191
	global_store_dwordx2 v106, v[188:189], s[22:23] offset:1024 sc1
	v_mul_f32_e32 v192, v192, v238
	v_mul_f32_e32 v193, v193, v238
	v_mul_f32_e32 v194, v194, v238
	v_mul_f32_e32 v195, v195, v238
	v_fma_f32 v192, v192, v60, v76
	v_fma_f32 v193, v193, v61, v77
	v_fma_f32 v194, v194, v62, v78
	v_fma_f32 v195, v195, v63, v79
	v_cvt_pk_bf16_f32 v192, v192, v193
	v_cvt_pk_bf16_f32 v193, v194, v195
	global_store_dwordx2 v106, v[192:193], s[22:23] offset:1536 sc1
	s_add_i32 s18, s18, s14
	s_lshl_b32 s20, s18, 11
	s_add_u32 s22, s12, s20
	s_addc_u32 s23, s13, 0
	v_mul_f32_e32 v86, v86, v239
	v_mul_f32_e32 v87, v87, v239
	v_mul_f32_e32 v88, v88, v239
	v_mul_f32_e32 v89, v89, v239
	v_fma_f32 v86, v86, v48, v64
	v_fma_f32 v87, v87, v49, v65
	v_fma_f32 v88, v88, v50, v66
	v_fma_f32 v89, v89, v51, v67
	v_cvt_pk_bf16_f32 v86, v86, v87
	v_cvt_pk_bf16_f32 v87, v88, v89
	global_store_dwordx2 v106, v[86:87], s[22:23] sc1
; __device__ __forceinline__ unsigned pk2(float lo, float hi) { f32x2_t v = {lo, hi}; bf16x2_t b = __builtin_convertvector(v, bf16x2_t); return __builtin_bit_cast(unsigned, b); }
; __device__ __forceinline__ void norm_mod_phase(const float* X, const float* ng, const float* mod, bf16* H, int G) {
;     ...
;             for (int r = 0; r < 4; ++r) { if (!has[r]) continue;
;                 const float rs = __builtin_amdgcn_rsqf(s[r] * (1.f / D) + EPSN); v2u* o8 = (v2u*)(H + (size_t)mr[r] * D) + lane;
; #pragma unroll
;                 for (int j = 0; j < 4; ++j) { const f32x4 h = v[r][j] * rs * gs[j] + sh[j]; o8[64 * j] = (v2u){pk2(h.x, h.y), pk2(h.z, h.w)}; } }
	v_mul_f32_e32 v90, v90, v239
	v_mul_f32_e32 v91, v91, v239
	v_mul_f32_e32 v92, v92, v239
	v_mul_f32_e32 v93, v93, v239
	v_fma_f32 v90, v90, v52, v68
	v_fma_f32 v91, v91, v53, v69
	v_fma_f32 v92, v92, v54, v70
	v_fma_f32 v93, v93, v55, v71
	v_cvt_pk_bf16_f32 v90, v90, v91
	v_cvt_pk_bf16_f32 v91, v92, v93
	global_store_dwordx2 v106, v[90:91], s[22:23] offset:512 sc1
	v_mul_f32_e32 v94, v94, v239
	v_mul_f32_e32 v95, v95, v239
	v_mul_f32_e32 v96, v96, v239
	v_mul_f32_e32 v97, v97, v239
	v_fma_f32 v94, v94, v56, v72
	v_fma_f32 v95, v95, v57, v73
	v_fma_f32 v96, v96, v58, v74
	v_fma_f32 v97, v97, v59, v75
	v_cvt_pk_bf16_f32 v94, v94, v95
	v_cvt_pk_bf16_f32 v95, v96, v97
	global_store_dwordx2 v106, v[94:95], s[22:23] offset:1024 sc1
	v_mul_f32_e32 v98, v98, v239
	v_mul_f32_e32 v99, v99, v239
	v_mul_f32_e32 v100, v100, v239
	v_mul_f32_e32 v101, v101, v239
	v_fma_f32 v98, v98, v60, v76
	v_fma_f32 v99, v99, v61, v77
	v_fma_f32 v100, v100, v62, v78
	v_fma_f32 v101, v101, v63, v79
	v_cvt_pk_bf16_f32 v98, v98, v99
	v_cvt_pk_bf16_f32 v99, v100, v101
	global_store_dwordx2 v106, v[98:99], s[22:23] offset:1536 sc1
	s_add_i32 s18, s18, s14
	s_lshl_b32 s20, s18, 11
	s_add_u32 s22, s12, s20
	s_addc_u32 s23, s13, 0
	v_mul_f32_e32 v218, v218, v240
	v_mul_f32_e32 v219, v219, v240
	v_mul_f32_e32 v220, v220, v240
	v_mul_f32_e32 v221, v221, v240
	v_fma_f32 v218, v218, v48, v64
	v_fma_f32 v219, v219, v49, v65
	v_fma_f32 v220, v220, v50, v66
	v_fma_f32 v221, v221, v51, v67
	v_cvt_pk_bf16_f32 v218, v218, v219
	v_cvt_pk_bf16_f32 v219, v220, v221
	global_store_dwordx2 v106, v[218:219], s[22:23] sc1
	v_mul_f32_e32 v222, v222, v240
	v_mul_f32_e32 v223, v223, v240
	v_mul_f32_e32 v224, v224, v240
	v_mul_f32_e32 v225, v225, v240
	v_fma_f32 v222, v222, v52, v68
	v_fma_f32 v223, v223, v53, v69
	v_fma_f32 v224, v224, v54, v70
	v_fma_f32 v225, v225, v55, v71
	v_cvt_pk_bf16_f32 v222, v222, v223
	v_cvt_pk_bf16_f32 v223, v224, v225
	global_store_dwordx2 v106, v[222:223], s[22:23] offset:512 sc1
	v_mul_f32_e32 v226, v226, v240
	v_mul_f32_e32 v227, v227, v240
	v_mul_f32_e32 v228, v228, v240
	v_mul_f32_e32 v229, v229, v240
	v_fma_f32 v226, v226, v56, v72
	v_fma_f32 v227, v227, v57, v73
	v_fma_f32 v228, v228, v58, v74
	v_fma_f32 v229, v229, v59, v75
	v_cvt_pk_bf16_f32 v226, v226, v227
	v_cvt_pk_bf16_f32 v227, v228, v229
	global_store_dwordx2 v106, v[226:227], s[22:23] offset:1024 sc1
	v_mul_f32_e32 v230, v230, v240
	v_mul_f32_e32 v231, v231, v240
	v_mul_f32_e32 v232, v232, v240
	v_mul_f32_e32 v233, v233, v240
	v_fma_f32 v230, v230, v60, v76
	v_fma_f32 v231, v231, v61, v77
	v_fma_f32 v232, v232, v62, v78
	v_fma_f32 v233, v233, v63, v79
	v_cvt_pk_bf16_f32 v230, v230, v231
	v_cvt_pk_bf16_f32 v231, v232, v233
	global_store_dwordx2 v106, v[230:231], s[22:23] offset:1536 sc1
	s_add_i32 s18, s18, s14
	s_lshl_b32 s20, s18, 11
	s_add_u32 s22, s12, s20
	s_addc_u32 s23, s13, 0
	v_mul_f32_e32 v196, v196, v241
	v_mul_f32_e32 v197, v197, v241
	v_mul_f32_e32 v198, v198, v241
	v_mul_f32_e32 v199, v199, v241
	v_fma_f32 v196, v196, v48, v64
	v_fma_f32 v197, v197, v49, v65
	v_fma_f32 v198, v198, v50, v66
	v_fma_f32 v199, v199, v51, v67
	v_cvt_pk_bf16_f32 v196, v196, v197
	v_cvt_pk_bf16_f32 v197, v198, v199
	global_store_dwordx2 v106, v[196:197], s[22:23] sc1
	v_mul_f32_e32 v200, v200, v241
	v_mul_f32_e32 v201, v201, v241
	v_mul_f32_e32 v202, v202, v241
	v_mul_f32_e32 v203, v203, v241
	v_fma_f32 v200, v200, v52, v68
	v_fma_f32 v201, v201, v53, v69
	v_fma_f32 v202, v202, v54, v70
	v_fma_f32 v203, v203, v55, v71
	v_cvt_pk_bf16_f32 v200, v200, v201
	v_cvt_pk_bf16_f32 v201, v202, v203
	global_store_dwordx2 v106, v[200:201], s[22:23] offset:512 sc1
	v_mul_f32_e32 v204, v204, v241
	v_mul_f32_e32 v205, v205, v241
	v_mul_f32_e32 v206, v206, v241
	v_mul_f32_e32 v207, v207, v241
	v_fma_f32 v204, v204, v56, v72
	v_fma_f32 v205, v205, v57, v73
	v_fma_f32 v206, v206, v58, v74
	v_fma_f32 v207, v207, v59, v75
	v_cvt_pk_bf16_f32 v204, v204, v205
	v_cvt_pk_bf16_f32 v205, v206, v207
	global_store_dwordx2 v106, v[204:205], s[22:23] offset:1024 sc1
	v_mul_f32_e32 v102, v102, v241
	v_mul_f32_e32 v103, v103, v241
	v_mul_f32_e32 v104, v104, v241
	v_mul_f32_e32 v105, v105, v241
	v_fma_f32 v102, v102, v60, v76
	v_fma_f32 v103, v103, v61, v77
	v_fma_f32 v104, v104, v62, v78
	v_fma_f32 v105, v105, v63, v79
	v_cvt_pk_bf16_f32 v102, v102, v103
	v_cvt_pk_bf16_f32 v103, v104, v105
	global_store_dwordx2 v106, v[102:103], s[22:23] offset:1536 sc1
	s_branch .LBB0_96
